# projection epilogue of the hyena-column tiles: half-waves paired with v_permlane32_swap so each lane stores 16 contiguous bytes of HYT (half as many store instructions / line pieces)
# speedup vs baseline: 1.1369x; 1.0078x over previous
.LBB0_362:
	s_andn2_b64 vcc, exec, s[20:21]
	s_cbranch_vccnz .LBB0_364
	v_ashrrev_i32_e32 v161, 2, v166
	v_or_b32_e32 v160, s18, v168
	v_and_b32_e32 v161, 0xfffff800, v161
	v_add3_u32 v168, v160, v199, v161
	v_add_u32_e32 v162, 0xfffff800, v168
	v_and_b32_e32 v164, 0x1f80, v166
	v_ashrrev_i32_e32 v163, 31, v162
	v_lshlrev_b64 v[162:163], 14, v[162:163]
	v_lshlrev_b32_e32 v164, 1, v164
	v_lshl_add_u64 v[162:163], s[0:1], 0, v[162:163]
	v_lshl_or_b32 v164, v200, 4, v164
	v_lshl_add_u64 v[162:163], v[162:163], 0, v[164:165]
	v_add_u32_e32 v168, 0xfffff820, v168
	v_ashrrev_i32_e32 v169, 31, v168
	v_lshlrev_b64 v[168:169], 14, v[168:169]
	v_lshl_add_u64 v[168:169], s[0:1], 0, v[168:169]
	v_lshl_add_u64 v[168:169], v[168:169], 0, v[164:165]
	v_cvt_pk_bf16_f32 v228, v112, v113
	v_cvt_pk_bf16_f32 v229, v114, v115
	v_cvt_pk_bf16_f32 v230, v116, v117
	v_cvt_pk_bf16_f32 v231, v118, v119
	s_nop 1
	v_permlane32_swap_b32_e32 v228, v230
	v_permlane32_swap_b32_e32 v229, v231
	global_store_dwordx4 v[162:163], v[228:231], off
	v_cvt_pk_bf16_f32 v232, v120, v121
	v_cvt_pk_bf16_f32 v233, v122, v123
	v_cvt_pk_bf16_f32 v234, v124, v125
	v_cvt_pk_bf16_f32 v235, v126, v127
	s_nop 1
	v_permlane32_swap_b32_e32 v232, v234
	v_permlane32_swap_b32_e32 v233, v235
	global_store_dwordx4 v[162:163], v[232:235], off offset:32
	v_cvt_pk_bf16_f32 v236, v96, v97
	v_cvt_pk_bf16_f32 v237, v98, v99
	v_cvt_pk_bf16_f32 v238, v100, v101
	v_cvt_pk_bf16_f32 v239, v102, v103
	s_nop 1
	v_permlane32_swap_b32_e32 v236, v238
	v_permlane32_swap_b32_e32 v237, v239
	global_store_dwordx4 v[168:169], v[236:239], off
	v_cvt_pk_bf16_f32 v240, v104, v105
	v_cvt_pk_bf16_f32 v241, v106, v107
	v_cvt_pk_bf16_f32 v242, v108, v109
	v_cvt_pk_bf16_f32 v243, v110, v111
	s_nop 1
	v_permlane32_swap_b32_e32 v240, v242
	v_permlane32_swap_b32_e32 v241, v243
	global_store_dwordx4 v[168:169], v[240:243], off offset:32
	v_cvt_pk_bf16_f32 v228, v80, v81
	v_cvt_pk_bf16_f32 v229, v82, v83
	v_cvt_pk_bf16_f32 v230, v84, v85
	v_cvt_pk_bf16_f32 v231, v86, v87
	s_nop 1
	v_permlane32_swap_b32_e32 v228, v230
	v_permlane32_swap_b32_e32 v229, v231
	global_store_dwordx4 v[162:163], v[228:231], off offset:64
	v_cvt_pk_bf16_f32 v232, v88, v89
	v_cvt_pk_bf16_f32 v233, v90, v91
	v_cvt_pk_bf16_f32 v234, v92, v93
	v_cvt_pk_bf16_f32 v235, v94, v95
	s_nop 1
	v_permlane32_swap_b32_e32 v232, v234
	v_permlane32_swap_b32_e32 v233, v235
	global_store_dwordx4 v[162:163], v[232:235], off offset:96
	v_cvt_pk_bf16_f32 v236, v64, v65
	v_cvt_pk_bf16_f32 v237, v66, v67
	v_cvt_pk_bf16_f32 v238, v68, v69
	v_cvt_pk_bf16_f32 v239, v70, v71
	s_nop 1
	v_permlane32_swap_b32_e32 v236, v238
	v_permlane32_swap_b32_e32 v237, v239
	global_store_dwordx4 v[168:169], v[236:239], off offset:64
	v_cvt_pk_bf16_f32 v240, v72, v73
	v_cvt_pk_bf16_f32 v241, v74, v75
	v_cvt_pk_bf16_f32 v242, v76, v77
	v_cvt_pk_bf16_f32 v243, v78, v79
	s_nop 1
	v_permlane32_swap_b32_e32 v240, v242
	v_permlane32_swap_b32_e32 v241, v243
	global_store_dwordx4 v[168:169], v[240:243], off offset:96
	v_cvt_pk_bf16_f32 v228, v48, v49
	v_cvt_pk_bf16_f32 v229, v50, v51
	v_cvt_pk_bf16_f32 v230, v52, v53
	v_cvt_pk_bf16_f32 v231, v54, v55
	s_nop 1
	v_permlane32_swap_b32_e32 v228, v230
	v_permlane32_swap_b32_e32 v229, v231
	global_store_dwordx4 v[162:163], v[228:231], off offset:128
	v_cvt_pk_bf16_f32 v232, v56, v57
	v_cvt_pk_bf16_f32 v233, v58, v59
	v_cvt_pk_bf16_f32 v234, v60, v61
	v_cvt_pk_bf16_f32 v235, v62, v63
	s_nop 1
	v_permlane32_swap_b32_e32 v232, v234
	v_permlane32_swap_b32_e32 v233, v235
	global_store_dwordx4 v[162:163], v[232:235], off offset:160
	v_cvt_pk_bf16_f32 v236, v32, v33
	v_cvt_pk_bf16_f32 v237, v34, v35
	v_cvt_pk_bf16_f32 v238, v36, v37
	v_cvt_pk_bf16_f32 v239, v38, v39
	s_nop 1
	v_permlane32_swap_b32_e32 v236, v238
	v_permlane32_swap_b32_e32 v237, v239
	global_store_dwordx4 v[168:169], v[236:239], off offset:128
	v_cvt_pk_bf16_f32 v240, v40, v41
	v_cvt_pk_bf16_f32 v241, v42, v43
	v_cvt_pk_bf16_f32 v242, v44, v45
	v_cvt_pk_bf16_f32 v243, v46, v47
	s_nop 1
	v_permlane32_swap_b32_e32 v240, v242
	v_permlane32_swap_b32_e32 v241, v243
	global_store_dwordx4 v[168:169], v[240:243], off offset:160
	v_cvt_pk_bf16_f32 v228, v16, v17
	v_cvt_pk_bf16_f32 v229, v18, v19
	v_cvt_pk_bf16_f32 v230, v20, v21
	v_cvt_pk_bf16_f32 v231, v22, v23
	s_nop 1
	v_permlane32_swap_b32_e32 v228, v230
	v_permlane32_swap_b32_e32 v229, v231
	global_store_dwordx4 v[162:163], v[228:231], off offset:192
	v_cvt_pk_bf16_f32 v232, v24, v25
	v_cvt_pk_bf16_f32 v233, v26, v27
	v_cvt_pk_bf16_f32 v234, v28, v29
	v_cvt_pk_bf16_f32 v235, v30, v31
	s_nop 1
	v_permlane32_swap_b32_e32 v232, v234
	v_permlane32_swap_b32_e32 v233, v235
	global_store_dwordx4 v[162:163], v[232:235], off offset:224
	v_cvt_pk_bf16_f32 v236, v0, v1
	v_cvt_pk_bf16_f32 v237, v2, v3
	v_cvt_pk_bf16_f32 v238, v4, v5
	v_cvt_pk_bf16_f32 v239, v6, v7
	s_nop 1
	v_permlane32_swap_b32_e32 v236, v238
	v_permlane32_swap_b32_e32 v237, v239
	global_store_dwordx4 v[168:169], v[236:239], off offset:192
	v_cvt_pk_bf16_f32 v240, v8, v9
	v_cvt_pk_bf16_f32 v241, v10, v11
	v_cvt_pk_bf16_f32 v242, v12, v13
	v_cvt_pk_bf16_f32 v243, v14, v15
	s_nop 1
	v_permlane32_swap_b32_e32 v240, v242
	v_permlane32_swap_b32_e32 v241, v243
	global_store_dwordx4 v[168:169], v[240:243], off offset:224

.LBB0_745:
	s_andn2_b64 vcc, exec, s[14:15]
	s_cbranch_vccnz .LBB0_747
	v_ashrrev_i32_e32 v161, 2, v166
	v_or_b32_e32 v160, s12, v168
	v_and_b32_e32 v161, 0xfffff800, v161
	v_add3_u32 v168, v160, v199, v161
	v_add_u32_e32 v162, 0xfffff800, v168
	v_and_b32_e32 v164, 0x1f80, v166
	v_ashrrev_i32_e32 v163, 31, v162
	v_lshlrev_b64 v[162:163], 14, v[162:163]
	v_lshlrev_b32_e32 v164, 1, v164
	v_lshl_add_u64 v[162:163], s[0:1], 0, v[162:163]
	v_lshl_or_b32 v164, v200, 4, v164
	v_lshl_add_u64 v[162:163], v[162:163], 0, v[164:165]
	v_add_u32_e32 v168, 0xfffff820, v168
	v_ashrrev_i32_e32 v169, 31, v168
	v_lshlrev_b64 v[168:169], 14, v[168:169]
	v_lshl_add_u64 v[168:169], s[0:1], 0, v[168:169]
	v_lshl_add_u64 v[168:169], v[168:169], 0, v[164:165]
	v_cvt_pk_bf16_f32 v228, v112, v113
	v_cvt_pk_bf16_f32 v229, v114, v115
	v_cvt_pk_bf16_f32 v230, v116, v117
	v_cvt_pk_bf16_f32 v231, v118, v119
	s_nop 1
	v_permlane32_swap_b32_e32 v228, v230
	v_permlane32_swap_b32_e32 v229, v231
	global_store_dwordx4 v[162:163], v[228:231], off
	v_cvt_pk_bf16_f32 v232, v120, v121
	v_cvt_pk_bf16_f32 v233, v122, v123
	v_cvt_pk_bf16_f32 v234, v124, v125
	v_cvt_pk_bf16_f32 v235, v126, v127
	s_nop 1
	v_permlane32_swap_b32_e32 v232, v234
	v_permlane32_swap_b32_e32 v233, v235
	global_store_dwordx4 v[162:163], v[232:235], off offset:32
	v_cvt_pk_bf16_f32 v236, v96, v97
	v_cvt_pk_bf16_f32 v237, v98, v99
	v_cvt_pk_bf16_f32 v238, v100, v101
	v_cvt_pk_bf16_f32 v239, v102, v103
	s_nop 1
	v_permlane32_swap_b32_e32 v236, v238
	v_permlane32_swap_b32_e32 v237, v239
	global_store_dwordx4 v[168:169], v[236:239], off
	v_cvt_pk_bf16_f32 v240, v104, v105
	v_cvt_pk_bf16_f32 v241, v106, v107
	v_cvt_pk_bf16_f32 v242, v108, v109
	v_cvt_pk_bf16_f32 v243, v110, v111
	s_nop 1
	v_permlane32_swap_b32_e32 v240, v242
	v_permlane32_swap_b32_e32 v241, v243
	global_store_dwordx4 v[168:169], v[240:243], off offset:32
	v_cvt_pk_bf16_f32 v228, v80, v81
	v_cvt_pk_bf16_f32 v229, v82, v83
	v_cvt_pk_bf16_f32 v230, v84, v85
	v_cvt_pk_bf16_f32 v231, v86, v87
	s_nop 1
	v_permlane32_swap_b32_e32 v228, v230
	v_permlane32_swap_b32_e32 v229, v231
	global_store_dwordx4 v[162:163], v[228:231], off offset:64
	v_cvt_pk_bf16_f32 v232, v88, v89
	v_cvt_pk_bf16_f32 v233, v90, v91
	v_cvt_pk_bf16_f32 v234, v92, v93
	v_cvt_pk_bf16_f32 v235, v94, v95
	s_nop 1
	v_permlane32_swap_b32_e32 v232, v234
	v_permlane32_swap_b32_e32 v233, v235
	global_store_dwordx4 v[162:163], v[232:235], off offset:96
	v_cvt_pk_bf16_f32 v236, v64, v65
	v_cvt_pk_bf16_f32 v237, v66, v67
	v_cvt_pk_bf16_f32 v238, v68, v69
	v_cvt_pk_bf16_f32 v239, v70, v71
	s_nop 1
	v_permlane32_swap_b32_e32 v236, v238
	v_permlane32_swap_b32_e32 v237, v239
	global_store_dwordx4 v[168:169], v[236:239], off offset:64
	v_cvt_pk_bf16_f32 v240, v72, v73
	v_cvt_pk_bf16_f32 v241, v74, v75
	v_cvt_pk_bf16_f32 v242, v76, v77
	v_cvt_pk_bf16_f32 v243, v78, v79
	s_nop 1
	v_permlane32_swap_b32_e32 v240, v242
	v_permlane32_swap_b32_e32 v241, v243
	global_store_dwordx4 v[168:169], v[240:243], off offset:96
	v_cvt_pk_bf16_f32 v228, v48, v49
	v_cvt_pk_bf16_f32 v229, v50, v51
	v_cvt_pk_bf16_f32 v230, v52, v53
	v_cvt_pk_bf16_f32 v231, v54, v55
	s_nop 1
	v_permlane32_swap_b32_e32 v228, v230
	v_permlane32_swap_b32_e32 v229, v231
	global_store_dwordx4 v[162:163], v[228:231], off offset:128
	v_cvt_pk_bf16_f32 v232, v56, v57
	v_cvt_pk_bf16_f32 v233, v58, v59
	v_cvt_pk_bf16_f32 v234, v60, v61
	v_cvt_pk_bf16_f32 v235, v62, v63
	s_nop 1
	v_permlane32_swap_b32_e32 v232, v234
	v_permlane32_swap_b32_e32 v233, v235
	global_store_dwordx4 v[162:163], v[232:235], off offset:160
	v_cvt_pk_bf16_f32 v236, v32, v33
	v_cvt_pk_bf16_f32 v237, v34, v35
	v_cvt_pk_bf16_f32 v238, v36, v37
	v_cvt_pk_bf16_f32 v239, v38, v39
	s_nop 1
	v_permlane32_swap_b32_e32 v236, v238
	v_permlane32_swap_b32_e32 v237, v239
	global_store_dwordx4 v[168:169], v[236:239], off offset:128
	v_cvt_pk_bf16_f32 v240, v40, v41
	v_cvt_pk_bf16_f32 v241, v42, v43
	v_cvt_pk_bf16_f32 v242, v44, v45
	v_cvt_pk_bf16_f32 v243, v46, v47
	s_nop 1
	v_permlane32_swap_b32_e32 v240, v242
	v_permlane32_swap_b32_e32 v241, v243
	global_store_dwordx4 v[168:169], v[240:243], off offset:160
	v_cvt_pk_bf16_f32 v228, v16, v17
	v_cvt_pk_bf16_f32 v229, v18, v19
	v_cvt_pk_bf16_f32 v230, v20, v21
	v_cvt_pk_bf16_f32 v231, v22, v23
	s_nop 1
	v_permlane32_swap_b32_e32 v228, v230
	v_permlane32_swap_b32_e32 v229, v231
	global_store_dwordx4 v[162:163], v[228:231], off offset:192
	v_cvt_pk_bf16_f32 v232, v24, v25
	v_cvt_pk_bf16_f32 v233, v26, v27
	v_cvt_pk_bf16_f32 v234, v28, v29
	v_cvt_pk_bf16_f32 v235, v30, v31
	s_nop 1
	v_permlane32_swap_b32_e32 v232, v234
	v_permlane32_swap_b32_e32 v233, v235
	global_store_dwordx4 v[162:163], v[232:235], off offset:224
	v_cvt_pk_bf16_f32 v236, v0, v1
	v_cvt_pk_bf16_f32 v237, v2, v3
	v_cvt_pk_bf16_f32 v238, v4, v5
	v_cvt_pk_bf16_f32 v239, v6, v7
	s_nop 1
	v_permlane32_swap_b32_e32 v236, v238
	v_permlane32_swap_b32_e32 v237, v239
	global_store_dwordx4 v[168:169], v[236:239], off offset:192
	v_cvt_pk_bf16_f32 v240, v8, v9
	v_cvt_pk_bf16_f32 v241, v10, v11
	v_cvt_pk_bf16_f32 v242, v12, v13
	v_cvt_pk_bf16_f32 v243, v14, v15
	s_nop 1
	v_permlane32_swap_b32_e32 v240, v242
	v_permlane32_swap_b32_e32 v241, v243
	global_store_dwordx4 v[168:169], v[240:243], off offset:224
